# ret_kv_item staging: K and V loads issued back-to-back with counted waits
# baseline (speedup 1.0000x reference)
; __device__ __forceinline__ u16 f2bf(float x) { return (u16)(cvtpk(x, 0.f) & 0xffffu); }
; __device__ __forceinline__ float bf2f(u16 v) { return __uint_as_float(((unsigned)v) << 16); }
; __device__ __forceinline__ void ret_kv_item(const P& p, int item, char* lds) {
;     ...
;   for (int e = tid; e < 128 * 8; e += NTHR) {
;     const int j = e >> 3, c8 = (e & 7) * 8;
;     const bf16x8 kv = *(const bf16x8*)(z + (tok0 + j) * ZC + C_RK + h * 64 + c8);
;     const bf16x8 vv = *(const bf16x8*)(z + (tok0 + j) * ZC + C_RV + h * 64 + c8);
;     const float df = exp2f(lg * (float)(127 - j)), db = exp2f(lg * (float)j);
; #pragma unroll
;     for (int q = 0; q < 8; ++q) {
;       const float kf = bf2f((u16)kv[q]);
;       KF[(c8 + q) * 136 + j] = f2bf(kf * df); KB[(c8 + q) * 136 + j] = f2bf(kf * db); VT[(c8 + q) * 136 + j] = (u16)vv[q];
;     }
;   }
.LBB0_295:
	v_ashrrev_i32_e32 v14, 3, v2
	v_ashrrev_i32_e32 v15, 31, v14
	v_lshl_add_u64 v[6:7], s[58:59], 0, v[14:15]
	v_mov_b64_e32 v[8:9], s[42:43]
	v_mad_u64_u32 v[8:9], s[64:65], v6, s9, v[8:9]
	v_mov_b32_e32 v6, v9
	v_mad_u64_u32 v[6:7], s[64:65], v7, s9, v[6:7]
	v_and_b32_e32 v3, 56, v1
	v_mov_b32_e32 v9, v6
	v_lshl_add_u64 v[6:7], v[8:9], 0, s[92:93]
	v_lshlrev_b32_e32 v200, 1, v3
	v_lshl_add_u64 v[10:11], v[6:7], 0, v[200:201]
	v_sub_u32_e32 v6, 0x7f, v14
	v_cvt_f32_u32_e32 v6, v6
	s_movk_i32 s7, 0x88
	v_mad_u32_u24 v3, v3, s7, v14
	v_lshl_add_u32 v3, v3, 1, 0
	v_mul_f32_e32 v7, v0, v6
	v_cmp_gt_f32_e32 vcc, s15, v7
	v_add_u32_e32 v1, 0x800, v1
	s_nop 0
	v_cndmask_b32_e32 v7, 0, v251, vcc
	v_fmac_f32_e32 v7, v0, v6
	v_exp_f32_e32 v6, v7
	v_cndmask_b32_e32 v7, 0, v222, vcc
	v_ldexp_f32 v15, v6, v7
	v_cvt_f32_i32_e32 v6, v14
	v_mul_f32_e32 v7, v0, v6
	v_cmp_gt_f32_e32 vcc, s15, v7
	s_nop 1
	v_cndmask_b32_e32 v7, 0, v251, vcc
	v_fmac_f32_e32 v7, v0, v6
	v_exp_f32_e32 v6, v7
	v_cndmask_b32_e32 v7, 0, v222, vcc
	v_ldexp_f32 v16, v6, v7
	global_load_dwordx4 v[6:9], v[10:11], off offset:3584
	v_add_co_u32_e32 v10, vcc, s10, v10
	s_nop 1
	v_addc_co_u32_e32 v11, vcc, 0, v11, vcc
	global_load_dwordx4 v[10:13], v[10:11], off
	s_waitcnt vmcnt(1)
	v_lshlrev_b32_e32 v17, 16, v6
	v_mul_f32_e32 v18, v15, v17
	v_mul_f32_e32 v14, v16, v17
	v_cvt_pk_bf16_f32 v18, v18, v201
	ds_write_b16 v3, v18 offset:17408
	v_cvt_pk_bf16_f32 v14, v14, v201
	v_and_b32_e32 v6, 0xffff0000, v6
	ds_write_b16 v3, v14 offset:34816
	s_waitcnt vmcnt(0)
	ds_write_b16 v3, v10
	v_mul_f32_e32 v14, v15, v6
	v_mul_f32_e32 v6, v16, v6
	v_cvt_pk_bf16_f32 v14, v14, v201
	ds_write_b16 v3, v14 offset:17680
	v_cvt_pk_bf16_f32 v6, v6, v201
	ds_write_b16 v3, v6 offset:35088
	ds_write_b16_d16_hi v3, v10 offset:272
	v_lshlrev_b32_e32 v6, 16, v7
	v_mul_f32_e32 v10, v15, v6
	v_mul_f32_e32 v6, v16, v6
	v_cvt_pk_bf16_f32 v10, v10, v201
	ds_write_b16 v3, v10 offset:17952
	v_cvt_pk_bf16_f32 v6, v6, v201
	ds_write_b16 v3, v6 offset:35360
	ds_write_b16 v3, v11 offset:544
	v_and_b32_e32 v6, 0xffff0000, v7
	v_mul_f32_e32 v7, v15, v6
	v_mul_f32_e32 v6, v16, v6
	v_cvt_pk_bf16_f32 v7, v7, v201
	ds_write_b16 v3, v7 offset:18224
	v_cvt_pk_bf16_f32 v6, v6, v201
	ds_write_b16 v3, v6 offset:35632
	ds_write_b16_d16_hi v3, v11 offset:816
	v_lshlrev_b32_e32 v6, 16, v8
	v_mul_f32_e32 v7, v15, v6
	v_mul_f32_e32 v6, v16, v6
	v_cvt_pk_bf16_f32 v7, v7, v201
	ds_write_b16 v3, v7 offset:18496
	v_cvt_pk_bf16_f32 v6, v6, v201
	ds_write_b16 v3, v6 offset:35904
	ds_write_b16 v3, v12 offset:1088
	v_and_b32_e32 v6, 0xffff0000, v8
	v_mul_f32_e32 v7, v15, v6
	v_mul_f32_e32 v6, v16, v6
	v_cvt_pk_bf16_f32 v7, v7, v201
	ds_write_b16 v3, v7 offset:18768
	v_cvt_pk_bf16_f32 v6, v6, v201
	ds_write_b16 v3, v6 offset:36176
	ds_write_b16_d16_hi v3, v12 offset:1360
	v_lshlrev_b32_e32 v6, 16, v9
	v_mul_f32_e32 v7, v15, v6
	v_mul_f32_e32 v6, v16, v6
	v_cvt_pk_bf16_f32 v7, v7, v201
	ds_write_b16 v3, v7 offset:19040
	v_cvt_pk_bf16_f32 v6, v6, v201
	ds_write_b16 v3, v6 offset:36448
	ds_write_b16 v3, v13 offset:1632
	v_and_b32_e32 v6, 0xffff0000, v9
	v_mul_f32_e32 v7, v15, v6
	v_mul_f32_e32 v6, v16, v6
	v_cvt_pk_bf16_f32 v7, v7, v201
	ds_write_b16 v3, v7 offset:19312
	v_cvt_pk_bf16_f32 v6, v6, v201
	ds_write_b16 v3, v6 offset:36720
	ds_write_b16_d16_hi v3, v13 offset:1904
	v_add_u32_e32 v3, 0x100, v2
	v_cmp_lt_i32_e32 vcc, s16, v2
	s_or_b64 s[62:63], vcc, s[62:63]
	v_mov_b32_e32 v2, v3
	s_andn2_b64 exec, exec, s[62:63]
	s_cbranch_execnz .LBB0_295
	s_branch .LBB0_290
